# EpiGlu epilogue (GLU gate GEMM) rewritten: G loads in flight instead of 16 serialised round trips, packed sigmoid, stores at end
# speedup vs baseline: 1.0038x; 1.0019x over previous
; __device__ __forceinline__ unsigned cvt_pk_bf16(float lo, float hi) { unsigned r; asm("v_cvt_pk_bf16_f32 %0, %1, %2" : "=v"(r) : "v"(lo), "v"(hi)); return r; }
; __device__ __forceinline__ float fast_sigmoid(float x) { return __builtin_amdgcn_rcpf(1.0f + __builtin_amdgcn_exp2f(-x * LOG2E)); }
;     __device__ __forceinline__ void operator()(const Acc& acc, const Unit& u, int wr, int wc, int fr, int fq) const {
;         const int row0 = u.pm * 256 + wr * 64 + fr, col0 = u.pn * 256 + wc * 32 + 8 * fq;
; #pragma unroll
;         for (int ai = 0; ai < 2; ++ai)
; #pragma unroll
;             for (int m = 0; m < 4; ++m) { const int row = row0 + ai * 128 + m * 16;
; #pragma unroll
;                 for (int bj = 0; bj < 2; ++bj) { const int col = col0 + bj * 128; const u32x4 gw = *(const u32x4*)(G + ((size_t)(col >> 4) * MX + row) * 16 + (col & 15)); const f32x4 a = acc[ai][bj][m][0], b = acc[ai][bj][m][1];
;                     u32x4 w; w.x = cvt_pk_bf16(bf2f(gw.x & 0xffffu) * fast_sigmoid(a[0]), bf2f(gw.x >> 16) * fast_sigmoid(a[1])); w.y = cvt_pk_bf16(bf2f(gw.y & 0xffffu) * fast_sigmoid(a[2]), bf2f(gw.y >> 16) * fast_sigmoid(a[3]));
;                     w.z = cvt_pk_bf16(bf2f(gw.z & 0xffffu) * fast_sigmoid(b[0]), bf2f(gw.z >> 16) * fast_sigmoid(b[1])); w.w = cvt_pk_bf16(bf2f(gw.w & 0xffffu) * fast_sigmoid(b[2]), bf2f(gw.w >> 16) * fast_sigmoid(b[3]));
;                     *(u32x4*)(MIX + (size_t)row * 1024 + 512 + col) = w; } }
.LBB0_845:
	v_lshl_or_b32 v216, s34, 8, v152
	v_lshrrev_b32_e32 v217, 4, v216
	v_lshlrev_b32_e32 v217, 20, v217
	v_lshl_add_u32 v218, s40, 8, v150
	v_lshl_add_u32 v217, v218, 5, v217
	v_add_u32_e32 v217, v217, v136
	v_add_u32_e32 v219, 0x800000, v217
	v_lshlrev_b32_e32 v218, 11, v218
	v_lshl_add_u32 v218, v216, 1, v218
	s_mov_b32 vcc_lo, 0xbfb8aa3b
	s_mov_b32 vcc_hi, 0xbfb8aa3b
	global_load_dwordx4 v[156:159], v217, s[0:1]
	global_load_dwordx4 v[160:163], v219, s[0:1]
	global_load_dwordx4 v[164:167], v217, s[0:1] offset:512
	global_load_dwordx4 v[168:171], v219, s[0:1] offset:512
	global_load_dwordx4 v[172:175], v217, s[0:1] offset:1024
	global_load_dwordx4 v[176:179], v219, s[0:1] offset:1024
	global_load_dwordx4 v[180:183], v217, s[0:1] offset:1536
	global_load_dwordx4 v[184:187], v219, s[0:1] offset:1536
	v_add_u32_e32 v217, 0x1000, v217
	v_add_u32_e32 v219, 0x1000, v219
	global_load_dwordx4 v[188:191], v217, s[0:1]
	global_load_dwordx4 v[192:195], v219, s[0:1]
	global_load_dwordx4 v[196:199], v217, s[0:1] offset:512
	global_load_dwordx4 v[200:203], v219, s[0:1] offset:512
	s_waitcnt vmcnt(11)
	v_lshlrev_b32_e32 v208, 16, v156
	v_and_b32_e32 v209, 0xffff0000, v156
	v_lshlrev_b32_e32 v210, 16, v157
	v_and_b32_e32 v211, 0xffff0000, v157
	v_lshlrev_b32_e32 v212, 16, v158
	v_and_b32_e32 v213, 0xffff0000, v158
	v_lshlrev_b32_e32 v214, 16, v159
	v_and_b32_e32 v215, 0xffff0000, v159
	v_pk_mul_f32 v[146:147], v[124:125], vcc
	v_pk_mul_f32 v[148:149], v[126:127], vcc
	v_exp_f32_e32 v146, v146
	v_exp_f32_e32 v147, v147
	v_exp_f32_e32 v148, v148
	v_exp_f32_e32 v149, v149
	v_pk_add_f32 v[146:147], v[146:147], 1.0 op_sel_hi:[1,0]
	v_pk_add_f32 v[148:149], v[148:149], 1.0 op_sel_hi:[1,0]
	v_rcp_f32_e32 v146, v146
	v_rcp_f32_e32 v147, v147
	v_rcp_f32_e32 v148, v148
	v_rcp_f32_e32 v149, v149
	v_pk_mul_f32 v[124:125], v[146:147], v[208:209]
	v_pk_mul_f32 v[126:127], v[148:149], v[210:211]
	v_pk_mul_f32 v[146:147], v[120:121], vcc
	v_pk_mul_f32 v[148:149], v[122:123], vcc
	v_exp_f32_e32 v146, v146
	v_exp_f32_e32 v147, v147
	v_exp_f32_e32 v148, v148
	v_exp_f32_e32 v149, v149
	v_pk_add_f32 v[146:147], v[146:147], 1.0 op_sel_hi:[1,0]
	v_pk_add_f32 v[148:149], v[148:149], 1.0 op_sel_hi:[1,0]
	v_rcp_f32_e32 v146, v146
	v_rcp_f32_e32 v147, v147
	v_rcp_f32_e32 v148, v148
	v_rcp_f32_e32 v149, v149
	v_pk_mul_f32 v[120:121], v[146:147], v[212:213]
	v_pk_mul_f32 v[122:123], v[148:149], v[214:215]
	v_cvt_pk_bf16_f32 v124, v124, v125
	v_cvt_pk_bf16_f32 v125, v126, v127
	v_cvt_pk_bf16_f32 v126, v120, v121
	v_cvt_pk_bf16_f32 v127, v122, v123
	s_waitcnt vmcnt(10)
	v_lshlrev_b32_e32 v208, 16, v160
	v_and_b32_e32 v209, 0xffff0000, v160
	v_lshlrev_b32_e32 v210, 16, v161
	v_and_b32_e32 v211, 0xffff0000, v161
	v_lshlrev_b32_e32 v212, 16, v162
	v_and_b32_e32 v213, 0xffff0000, v162
	v_lshlrev_b32_e32 v214, 16, v163
	v_and_b32_e32 v215, 0xffff0000, v163
	v_pk_mul_f32 v[146:147], v[116:117], vcc
	v_pk_mul_f32 v[148:149], v[118:119], vcc
	v_exp_f32_e32 v146, v146
	v_exp_f32_e32 v147, v147
	v_exp_f32_e32 v148, v148
	v_exp_f32_e32 v149, v149
	v_pk_add_f32 v[146:147], v[146:147], 1.0 op_sel_hi:[1,0]
	v_pk_add_f32 v[148:149], v[148:149], 1.0 op_sel_hi:[1,0]
	v_rcp_f32_e32 v146, v146
	v_rcp_f32_e32 v147, v147
	v_rcp_f32_e32 v148, v148
	v_rcp_f32_e32 v149, v149
	v_pk_mul_f32 v[116:117], v[146:147], v[208:209]
	v_pk_mul_f32 v[118:119], v[148:149], v[210:211]
	v_pk_mul_f32 v[146:147], v[112:113], vcc
	v_pk_mul_f32 v[148:149], v[114:115], vcc
	v_exp_f32_e32 v146, v146
	v_exp_f32_e32 v147, v147
	v_exp_f32_e32 v148, v148
	v_exp_f32_e32 v149, v149
	v_pk_add_f32 v[146:147], v[146:147], 1.0 op_sel_hi:[1,0]
	v_pk_add_f32 v[148:149], v[148:149], 1.0 op_sel_hi:[1,0]
	v_rcp_f32_e32 v146, v146
	v_rcp_f32_e32 v147, v147
	v_rcp_f32_e32 v148, v148
	v_rcp_f32_e32 v149, v149
	v_pk_mul_f32 v[112:113], v[146:147], v[212:213]
	v_pk_mul_f32 v[114:115], v[148:149], v[214:215]
	v_cvt_pk_bf16_f32 v116, v116, v117
	v_cvt_pk_bf16_f32 v117, v118, v119
	v_cvt_pk_bf16_f32 v118, v112, v113
	v_cvt_pk_bf16_f32 v119, v114, v115
	s_waitcnt vmcnt(9)
	v_lshlrev_b32_e32 v208, 16, v164
	v_and_b32_e32 v209, 0xffff0000, v164
	v_lshlrev_b32_e32 v210, 16, v165
	v_and_b32_e32 v211, 0xffff0000, v165
	v_lshlrev_b32_e32 v212, 16, v166
	v_and_b32_e32 v213, 0xffff0000, v166
	v_lshlrev_b32_e32 v214, 16, v167
	v_and_b32_e32 v215, 0xffff0000, v167
	v_pk_mul_f32 v[146:147], v[108:109], vcc
	v_pk_mul_f32 v[148:149], v[110:111], vcc
	v_exp_f32_e32 v146, v146
	v_exp_f32_e32 v147, v147
	v_exp_f32_e32 v148, v148
	v_exp_f32_e32 v149, v149
	v_pk_add_f32 v[146:147], v[146:147], 1.0 op_sel_hi:[1,0]
	v_pk_add_f32 v[148:149], v[148:149], 1.0 op_sel_hi:[1,0]
	v_rcp_f32_e32 v146, v146
	v_rcp_f32_e32 v147, v147
	v_rcp_f32_e32 v148, v148
	v_rcp_f32_e32 v149, v149
	v_pk_mul_f32 v[108:109], v[146:147], v[208:209]
	v_pk_mul_f32 v[110:111], v[148:149], v[210:211]
	v_pk_mul_f32 v[146:147], v[104:105], vcc
	v_pk_mul_f32 v[148:149], v[106:107], vcc
	v_exp_f32_e32 v146, v146
	v_exp_f32_e32 v147, v147
	v_exp_f32_e32 v148, v148
	v_exp_f32_e32 v149, v149
	v_pk_add_f32 v[146:147], v[146:147], 1.0 op_sel_hi:[1,0]
	v_pk_add_f32 v[148:149], v[148:149], 1.0 op_sel_hi:[1,0]
	v_rcp_f32_e32 v146, v146
	v_rcp_f32_e32 v147, v147
	v_rcp_f32_e32 v148, v148
	v_rcp_f32_e32 v149, v149
	v_pk_mul_f32 v[104:105], v[146:147], v[212:213]
	v_pk_mul_f32 v[106:107], v[148:149], v[214:215]
	v_cvt_pk_bf16_f32 v108, v108, v109
	v_cvt_pk_bf16_f32 v109, v110, v111
	v_cvt_pk_bf16_f32 v110, v104, v105
	v_cvt_pk_bf16_f32 v111, v106, v107
	s_waitcnt vmcnt(8)
; __device__ __forceinline__ unsigned cvt_pk_bf16(float lo, float hi) { unsigned r; asm("v_cvt_pk_bf16_f32 %0, %1, %2" : "=v"(r) : "v"(lo), "v"(hi)); return r; }
; __device__ __forceinline__ float fast_sigmoid(float x) { return __builtin_amdgcn_rcpf(1.0f + __builtin_amdgcn_exp2f(-x * LOG2E)); }
;     __device__ __forceinline__ void operator()(const Acc& acc, const Unit& u, int wr, int wc, int fr, int fq) const {
;         const int row0 = u.pm * 256 + wr * 64 + fr, col0 = u.pn * 256 + wc * 32 + 8 * fq;
; #pragma unroll
;         for (int ai = 0; ai < 2; ++ai)
; #pragma unroll
;             for (int m = 0; m < 4; ++m) { const int row = row0 + ai * 128 + m * 16;
; #pragma unroll
;                 for (int bj = 0; bj < 2; ++bj) { const int col = col0 + bj * 128; const u32x4 gw = *(const u32x4*)(G + ((size_t)(col >> 4) * MX + row) * 16 + (col & 15)); const f32x4 a = acc[ai][bj][m][0], b = acc[ai][bj][m][1];
;                     u32x4 w; w.x = cvt_pk_bf16(bf2f(gw.x & 0xffffu) * fast_sigmoid(a[0]), bf2f(gw.x >> 16) * fast_sigmoid(a[1])); w.y = cvt_pk_bf16(bf2f(gw.y & 0xffffu) * fast_sigmoid(a[2]), bf2f(gw.y >> 16) * fast_sigmoid(a[3]));
;                     w.z = cvt_pk_bf16(bf2f(gw.z & 0xffffu) * fast_sigmoid(b[0]), bf2f(gw.z >> 16) * fast_sigmoid(b[1])); w.w = cvt_pk_bf16(bf2f(gw.w & 0xffffu) * fast_sigmoid(b[2]), bf2f(gw.w >> 16) * fast_sigmoid(b[3]));
;                     *(u32x4*)(MIX + (size_t)row * 1024 + 512 + col) = w; } }
	v_lshlrev_b32_e32 v208, 16, v168
	v_and_b32_e32 v209, 0xffff0000, v168
	v_lshlrev_b32_e32 v210, 16, v169
	v_and_b32_e32 v211, 0xffff0000, v169
	v_lshlrev_b32_e32 v212, 16, v170
	v_and_b32_e32 v213, 0xffff0000, v170
	v_lshlrev_b32_e32 v214, 16, v171
	v_and_b32_e32 v215, 0xffff0000, v171
	global_load_dwordx4 v[156:159], v217, s[0:1] offset:1024
	global_load_dwordx4 v[160:163], v219, s[0:1] offset:1024
	global_load_dwordx4 v[164:167], v217, s[0:1] offset:1536
	global_load_dwordx4 v[168:171], v219, s[0:1] offset:1536
	v_pk_mul_f32 v[146:147], v[100:101], vcc
	v_pk_mul_f32 v[148:149], v[102:103], vcc
	v_exp_f32_e32 v146, v146
	v_exp_f32_e32 v147, v147
	v_exp_f32_e32 v148, v148
	v_exp_f32_e32 v149, v149
	v_pk_add_f32 v[146:147], v[146:147], 1.0 op_sel_hi:[1,0]
	v_pk_add_f32 v[148:149], v[148:149], 1.0 op_sel_hi:[1,0]
	v_rcp_f32_e32 v146, v146
	v_rcp_f32_e32 v147, v147
	v_rcp_f32_e32 v148, v148
	v_rcp_f32_e32 v149, v149
	v_pk_mul_f32 v[100:101], v[146:147], v[208:209]
	v_pk_mul_f32 v[102:103], v[148:149], v[210:211]
	v_pk_mul_f32 v[146:147], v[96:97], vcc
	v_pk_mul_f32 v[148:149], v[98:99], vcc
	v_exp_f32_e32 v146, v146
	v_exp_f32_e32 v147, v147
	v_exp_f32_e32 v148, v148
	v_exp_f32_e32 v149, v149
	v_pk_add_f32 v[146:147], v[146:147], 1.0 op_sel_hi:[1,0]
	v_pk_add_f32 v[148:149], v[148:149], 1.0 op_sel_hi:[1,0]
	v_rcp_f32_e32 v146, v146
	v_rcp_f32_e32 v147, v147
	v_rcp_f32_e32 v148, v148
	v_rcp_f32_e32 v149, v149
	v_pk_mul_f32 v[96:97], v[146:147], v[212:213]
	v_pk_mul_f32 v[98:99], v[148:149], v[214:215]
	v_cvt_pk_bf16_f32 v100, v100, v101
	v_cvt_pk_bf16_f32 v101, v102, v103
	v_cvt_pk_bf16_f32 v102, v96, v97
	v_cvt_pk_bf16_f32 v103, v98, v99
	s_waitcnt vmcnt(11)
	v_lshlrev_b32_e32 v208, 16, v172
	v_and_b32_e32 v209, 0xffff0000, v172
	v_lshlrev_b32_e32 v210, 16, v173
	v_and_b32_e32 v211, 0xffff0000, v173
	v_lshlrev_b32_e32 v212, 16, v174
	v_and_b32_e32 v213, 0xffff0000, v174
	v_lshlrev_b32_e32 v214, 16, v175
	v_and_b32_e32 v215, 0xffff0000, v175
	v_pk_mul_f32 v[146:147], v[92:93], vcc
	v_pk_mul_f32 v[148:149], v[94:95], vcc
	v_exp_f32_e32 v146, v146
	v_exp_f32_e32 v147, v147
	v_exp_f32_e32 v148, v148
	v_exp_f32_e32 v149, v149
	v_pk_add_f32 v[146:147], v[146:147], 1.0 op_sel_hi:[1,0]
	v_pk_add_f32 v[148:149], v[148:149], 1.0 op_sel_hi:[1,0]
	v_rcp_f32_e32 v146, v146
	v_rcp_f32_e32 v147, v147
	v_rcp_f32_e32 v148, v148
	v_rcp_f32_e32 v149, v149
	v_pk_mul_f32 v[92:93], v[146:147], v[208:209]
	v_pk_mul_f32 v[94:95], v[148:149], v[210:211]
	v_pk_mul_f32 v[146:147], v[88:89], vcc
	v_pk_mul_f32 v[148:149], v[90:91], vcc
	v_exp_f32_e32 v146, v146
	v_exp_f32_e32 v147, v147
	v_exp_f32_e32 v148, v148
	v_exp_f32_e32 v149, v149
	v_pk_add_f32 v[146:147], v[146:147], 1.0 op_sel_hi:[1,0]
	v_pk_add_f32 v[148:149], v[148:149], 1.0 op_sel_hi:[1,0]
	v_rcp_f32_e32 v146, v146
	v_rcp_f32_e32 v147, v147
	v_rcp_f32_e32 v148, v148
	v_rcp_f32_e32 v149, v149
	v_pk_mul_f32 v[88:89], v[146:147], v[212:213]
	v_pk_mul_f32 v[90:91], v[148:149], v[214:215]
	v_cvt_pk_bf16_f32 v92, v92, v93
	v_cvt_pk_bf16_f32 v93, v94, v95
	v_cvt_pk_bf16_f32 v94, v88, v89
	v_cvt_pk_bf16_f32 v95, v90, v91
	s_waitcnt vmcnt(10)
	v_lshlrev_b32_e32 v208, 16, v176
	v_and_b32_e32 v209, 0xffff0000, v176
	v_lshlrev_b32_e32 v210, 16, v177
	v_and_b32_e32 v211, 0xffff0000, v177
	v_lshlrev_b32_e32 v212, 16, v178
	v_and_b32_e32 v213, 0xffff0000, v178
	v_lshlrev_b32_e32 v214, 16, v179
	v_and_b32_e32 v215, 0xffff0000, v179
	v_pk_mul_f32 v[146:147], v[84:85], vcc
	v_pk_mul_f32 v[148:149], v[86:87], vcc
	v_exp_f32_e32 v146, v146
	v_exp_f32_e32 v147, v147
	v_exp_f32_e32 v148, v148
	v_exp_f32_e32 v149, v149
	v_pk_add_f32 v[146:147], v[146:147], 1.0 op_sel_hi:[1,0]
	v_pk_add_f32 v[148:149], v[148:149], 1.0 op_sel_hi:[1,0]
	v_rcp_f32_e32 v146, v146
	v_rcp_f32_e32 v147, v147
	v_rcp_f32_e32 v148, v148
	v_rcp_f32_e32 v149, v149
	v_pk_mul_f32 v[84:85], v[146:147], v[208:209]
	v_pk_mul_f32 v[86:87], v[148:149], v[210:211]
	v_pk_mul_f32 v[146:147], v[80:81], vcc
	v_pk_mul_f32 v[148:149], v[82:83], vcc
	v_exp_f32_e32 v146, v146
	v_exp_f32_e32 v147, v147
	v_exp_f32_e32 v148, v148
	v_exp_f32_e32 v149, v149
	v_pk_add_f32 v[146:147], v[146:147], 1.0 op_sel_hi:[1,0]
	v_pk_add_f32 v[148:149], v[148:149], 1.0 op_sel_hi:[1,0]
	v_rcp_f32_e32 v146, v146
	v_rcp_f32_e32 v147, v147
	v_rcp_f32_e32 v148, v148
	v_rcp_f32_e32 v149, v149
	v_pk_mul_f32 v[80:81], v[146:147], v[212:213]
	v_pk_mul_f32 v[82:83], v[148:149], v[214:215]
	v_cvt_pk_bf16_f32 v84, v84, v85
	v_cvt_pk_bf16_f32 v85, v86, v87
	v_cvt_pk_bf16_f32 v86, v80, v81
	v_cvt_pk_bf16_f32 v87, v82, v83
	s_waitcnt vmcnt(9)
	v_lshlrev_b32_e32 v208, 16, v180
	v_and_b32_e32 v209, 0xffff0000, v180
	v_lshlrev_b32_e32 v210, 16, v181
	v_and_b32_e32 v211, 0xffff0000, v181
	v_lshlrev_b32_e32 v212, 16, v182
	v_and_b32_e32 v213, 0xffff0000, v182
	v_lshlrev_b32_e32 v214, 16, v183
	v_and_b32_e32 v215, 0xffff0000, v183
	v_pk_mul_f32 v[146:147], v[76:77], vcc
	v_pk_mul_f32 v[148:149], v[78:79], vcc
	v_exp_f32_e32 v146, v146
	v_exp_f32_e32 v147, v147
	v_exp_f32_e32 v148, v148
	v_exp_f32_e32 v149, v149
	v_pk_add_f32 v[146:147], v[146:147], 1.0 op_sel_hi:[1,0]
	v_pk_add_f32 v[148:149], v[148:149], 1.0 op_sel_hi:[1,0]
	v_rcp_f32_e32 v146, v146
	v_rcp_f32_e32 v147, v147
	v_rcp_f32_e32 v148, v148
	v_rcp_f32_e32 v149, v149
	v_pk_mul_f32 v[76:77], v[146:147], v[208:209]
	v_pk_mul_f32 v[78:79], v[148:149], v[210:211]
	v_pk_mul_f32 v[146:147], v[72:73], vcc
	v_pk_mul_f32 v[148:149], v[74:75], vcc
	v_exp_f32_e32 v146, v146
	v_exp_f32_e32 v147, v147
	v_exp_f32_e32 v148, v148
	v_exp_f32_e32 v149, v149
	v_pk_add_f32 v[146:147], v[146:147], 1.0 op_sel_hi:[1,0]
	v_pk_add_f32 v[148:149], v[148:149], 1.0 op_sel_hi:[1,0]
	v_rcp_f32_e32 v146, v146
	v_rcp_f32_e32 v147, v147
	v_rcp_f32_e32 v148, v148
	v_rcp_f32_e32 v149, v149
	v_pk_mul_f32 v[72:73], v[146:147], v[212:213]
	v_pk_mul_f32 v[74:75], v[148:149], v[214:215]
	v_cvt_pk_bf16_f32 v76, v76, v77
	v_cvt_pk_bf16_f32 v77, v78, v79
	v_cvt_pk_bf16_f32 v78, v72, v73
	v_cvt_pk_bf16_f32 v79, v74, v75
	s_waitcnt vmcnt(8)
; __device__ __forceinline__ unsigned cvt_pk_bf16(float lo, float hi) { unsigned r; asm("v_cvt_pk_bf16_f32 %0, %1, %2" : "=v"(r) : "v"(lo), "v"(hi)); return r; }
; __device__ __forceinline__ float fast_sigmoid(float x) { return __builtin_amdgcn_rcpf(1.0f + __builtin_amdgcn_exp2f(-x * LOG2E)); }
;     __device__ __forceinline__ void operator()(const Acc& acc, const Unit& u, int wr, int wc, int fr, int fq) const {
;         const int row0 = u.pm * 256 + wr * 64 + fr, col0 = u.pn * 256 + wc * 32 + 8 * fq;
; #pragma unroll
;         for (int ai = 0; ai < 2; ++ai)
; #pragma unroll
;             for (int m = 0; m < 4; ++m) { const int row = row0 + ai * 128 + m * 16;
; #pragma unroll
;                 for (int bj = 0; bj < 2; ++bj) { const int col = col0 + bj * 128; const u32x4 gw = *(const u32x4*)(G + ((size_t)(col >> 4) * MX + row) * 16 + (col & 15)); const f32x4 a = acc[ai][bj][m][0], b = acc[ai][bj][m][1];
;                     u32x4 w; w.x = cvt_pk_bf16(bf2f(gw.x & 0xffffu) * fast_sigmoid(a[0]), bf2f(gw.x >> 16) * fast_sigmoid(a[1])); w.y = cvt_pk_bf16(bf2f(gw.y & 0xffffu) * fast_sigmoid(a[2]), bf2f(gw.y >> 16) * fast_sigmoid(a[3]));
;                     w.z = cvt_pk_bf16(bf2f(gw.z & 0xffffu) * fast_sigmoid(b[0]), bf2f(gw.z >> 16) * fast_sigmoid(b[1])); w.w = cvt_pk_bf16(bf2f(gw.w & 0xffffu) * fast_sigmoid(b[2]), bf2f(gw.w >> 16) * fast_sigmoid(b[3]));
;                     *(u32x4*)(MIX + (size_t)row * 1024 + 512 + col) = w; } }
	v_lshlrev_b32_e32 v208, 16, v184
	v_and_b32_e32 v209, 0xffff0000, v184
	v_lshlrev_b32_e32 v210, 16, v185
	v_and_b32_e32 v211, 0xffff0000, v185
	v_lshlrev_b32_e32 v212, 16, v186
	v_and_b32_e32 v213, 0xffff0000, v186
	v_lshlrev_b32_e32 v214, 16, v187
	v_and_b32_e32 v215, 0xffff0000, v187
	v_pk_mul_f32 v[146:147], v[68:69], vcc
	v_pk_mul_f32 v[148:149], v[70:71], vcc
	v_exp_f32_e32 v146, v146
	v_exp_f32_e32 v147, v147
	v_exp_f32_e32 v148, v148
	v_exp_f32_e32 v149, v149
	v_pk_add_f32 v[146:147], v[146:147], 1.0 op_sel_hi:[1,0]
	v_pk_add_f32 v[148:149], v[148:149], 1.0 op_sel_hi:[1,0]
	v_rcp_f32_e32 v146, v146
	v_rcp_f32_e32 v147, v147
	v_rcp_f32_e32 v148, v148
	v_rcp_f32_e32 v149, v149
	v_pk_mul_f32 v[68:69], v[146:147], v[208:209]
	v_pk_mul_f32 v[70:71], v[148:149], v[210:211]
	v_pk_mul_f32 v[146:147], v[64:65], vcc
	v_pk_mul_f32 v[148:149], v[66:67], vcc
	v_exp_f32_e32 v146, v146
	v_exp_f32_e32 v147, v147
	v_exp_f32_e32 v148, v148
	v_exp_f32_e32 v149, v149
	v_pk_add_f32 v[146:147], v[146:147], 1.0 op_sel_hi:[1,0]
	v_pk_add_f32 v[148:149], v[148:149], 1.0 op_sel_hi:[1,0]
	v_rcp_f32_e32 v146, v146
	v_rcp_f32_e32 v147, v147
	v_rcp_f32_e32 v148, v148
	v_rcp_f32_e32 v149, v149
	v_pk_mul_f32 v[64:65], v[146:147], v[212:213]
	v_pk_mul_f32 v[66:67], v[148:149], v[214:215]
	v_cvt_pk_bf16_f32 v68, v68, v69
	v_cvt_pk_bf16_f32 v69, v70, v71
	v_cvt_pk_bf16_f32 v70, v64, v65
	v_cvt_pk_bf16_f32 v71, v66, v67
	s_waitcnt vmcnt(7)
	v_lshlrev_b32_e32 v208, 16, v188
	v_and_b32_e32 v209, 0xffff0000, v188
	v_lshlrev_b32_e32 v210, 16, v189
	v_and_b32_e32 v211, 0xffff0000, v189
	v_lshlrev_b32_e32 v212, 16, v190
	v_and_b32_e32 v213, 0xffff0000, v190
	v_lshlrev_b32_e32 v214, 16, v191
	v_and_b32_e32 v215, 0xffff0000, v191
	v_pk_mul_f32 v[146:147], v[60:61], vcc
	v_pk_mul_f32 v[148:149], v[62:63], vcc
	v_exp_f32_e32 v146, v146
	v_exp_f32_e32 v147, v147
	v_exp_f32_e32 v148, v148
	v_exp_f32_e32 v149, v149
	v_pk_add_f32 v[146:147], v[146:147], 1.0 op_sel_hi:[1,0]
	v_pk_add_f32 v[148:149], v[148:149], 1.0 op_sel_hi:[1,0]
	v_rcp_f32_e32 v146, v146
	v_rcp_f32_e32 v147, v147
	v_rcp_f32_e32 v148, v148
	v_rcp_f32_e32 v149, v149
	v_pk_mul_f32 v[60:61], v[146:147], v[208:209]
	v_pk_mul_f32 v[62:63], v[148:149], v[210:211]
	v_pk_mul_f32 v[146:147], v[56:57], vcc
	v_pk_mul_f32 v[148:149], v[58:59], vcc
	v_exp_f32_e32 v146, v146
	v_exp_f32_e32 v147, v147
	v_exp_f32_e32 v148, v148
	v_exp_f32_e32 v149, v149
	v_pk_add_f32 v[146:147], v[146:147], 1.0 op_sel_hi:[1,0]
	v_pk_add_f32 v[148:149], v[148:149], 1.0 op_sel_hi:[1,0]
	v_rcp_f32_e32 v146, v146
	v_rcp_f32_e32 v147, v147
	v_rcp_f32_e32 v148, v148
	v_rcp_f32_e32 v149, v149
	v_pk_mul_f32 v[56:57], v[146:147], v[212:213]
	v_pk_mul_f32 v[58:59], v[148:149], v[214:215]
	v_cvt_pk_bf16_f32 v60, v60, v61
	v_cvt_pk_bf16_f32 v61, v62, v63
	v_cvt_pk_bf16_f32 v62, v56, v57
	v_cvt_pk_bf16_f32 v63, v58, v59
	s_waitcnt vmcnt(6)
	v_lshlrev_b32_e32 v208, 16, v192
	v_and_b32_e32 v209, 0xffff0000, v192
	v_lshlrev_b32_e32 v210, 16, v193
	v_and_b32_e32 v211, 0xffff0000, v193
	v_lshlrev_b32_e32 v212, 16, v194
	v_and_b32_e32 v213, 0xffff0000, v194
	v_lshlrev_b32_e32 v214, 16, v195
	v_and_b32_e32 v215, 0xffff0000, v195
	v_pk_mul_f32 v[146:147], v[52:53], vcc
	v_pk_mul_f32 v[148:149], v[54:55], vcc
	v_exp_f32_e32 v146, v146
	v_exp_f32_e32 v147, v147
	v_exp_f32_e32 v148, v148
	v_exp_f32_e32 v149, v149
	v_pk_add_f32 v[146:147], v[146:147], 1.0 op_sel_hi:[1,0]
	v_pk_add_f32 v[148:149], v[148:149], 1.0 op_sel_hi:[1,0]
	v_rcp_f32_e32 v146, v146
	v_rcp_f32_e32 v147, v147
	v_rcp_f32_e32 v148, v148
	v_rcp_f32_e32 v149, v149
	v_pk_mul_f32 v[52:53], v[146:147], v[208:209]
	v_pk_mul_f32 v[54:55], v[148:149], v[210:211]
	v_pk_mul_f32 v[146:147], v[48:49], vcc
	v_pk_mul_f32 v[148:149], v[50:51], vcc
	v_exp_f32_e32 v146, v146
	v_exp_f32_e32 v147, v147
	v_exp_f32_e32 v148, v148
	v_exp_f32_e32 v149, v149
	v_pk_add_f32 v[146:147], v[146:147], 1.0 op_sel_hi:[1,0]
	v_pk_add_f32 v[148:149], v[148:149], 1.0 op_sel_hi:[1,0]
	v_rcp_f32_e32 v146, v146
	v_rcp_f32_e32 v147, v147
	v_rcp_f32_e32 v148, v148
	v_rcp_f32_e32 v149, v149
	v_pk_mul_f32 v[48:49], v[146:147], v[212:213]
	v_pk_mul_f32 v[50:51], v[148:149], v[214:215]
	v_cvt_pk_bf16_f32 v52, v52, v53
	v_cvt_pk_bf16_f32 v53, v54, v55
	v_cvt_pk_bf16_f32 v54, v48, v49
	v_cvt_pk_bf16_f32 v55, v50, v51
	s_waitcnt vmcnt(5)
	v_lshlrev_b32_e32 v208, 16, v196
	v_and_b32_e32 v209, 0xffff0000, v196
	v_lshlrev_b32_e32 v210, 16, v197
	v_and_b32_e32 v211, 0xffff0000, v197
	v_lshlrev_b32_e32 v212, 16, v198
	v_and_b32_e32 v213, 0xffff0000, v198
	v_lshlrev_b32_e32 v214, 16, v199
	v_and_b32_e32 v215, 0xffff0000, v199
	v_pk_mul_f32 v[146:147], v[44:45], vcc
	v_pk_mul_f32 v[148:149], v[46:47], vcc
	v_exp_f32_e32 v146, v146
	v_exp_f32_e32 v147, v147
	v_exp_f32_e32 v148, v148
	v_exp_f32_e32 v149, v149
	v_pk_add_f32 v[146:147], v[146:147], 1.0 op_sel_hi:[1,0]
	v_pk_add_f32 v[148:149], v[148:149], 1.0 op_sel_hi:[1,0]
	v_rcp_f32_e32 v146, v146
	v_rcp_f32_e32 v147, v147
	v_rcp_f32_e32 v148, v148
	v_rcp_f32_e32 v149, v149
	v_pk_mul_f32 v[44:45], v[146:147], v[208:209]
	v_pk_mul_f32 v[46:47], v[148:149], v[210:211]
	v_pk_mul_f32 v[146:147], v[40:41], vcc
	v_pk_mul_f32 v[148:149], v[42:43], vcc
	v_exp_f32_e32 v146, v146
	v_exp_f32_e32 v147, v147
	v_exp_f32_e32 v148, v148
	v_exp_f32_e32 v149, v149
	v_pk_add_f32 v[146:147], v[146:147], 1.0 op_sel_hi:[1,0]
	v_pk_add_f32 v[148:149], v[148:149], 1.0 op_sel_hi:[1,0]
	v_rcp_f32_e32 v146, v146
	v_rcp_f32_e32 v147, v147
	v_rcp_f32_e32 v148, v148
	v_rcp_f32_e32 v149, v149
	v_pk_mul_f32 v[40:41], v[146:147], v[212:213]
	v_pk_mul_f32 v[42:43], v[148:149], v[214:215]
	v_cvt_pk_bf16_f32 v44, v44, v45
	v_cvt_pk_bf16_f32 v45, v46, v47
	v_cvt_pk_bf16_f32 v46, v40, v41
	v_cvt_pk_bf16_f32 v47, v42, v43
	s_waitcnt vmcnt(4)
; __device__ __forceinline__ unsigned cvt_pk_bf16(float lo, float hi) { unsigned r; asm("v_cvt_pk_bf16_f32 %0, %1, %2" : "=v"(r) : "v"(lo), "v"(hi)); return r; }
; __device__ __forceinline__ float fast_sigmoid(float x) { return __builtin_amdgcn_rcpf(1.0f + __builtin_amdgcn_exp2f(-x * LOG2E)); }
;     __device__ __forceinline__ void operator()(const Acc& acc, const Unit& u, int wr, int wc, int fr, int fq) const {
;         const int row0 = u.pm * 256 + wr * 64 + fr, col0 = u.pn * 256 + wc * 32 + 8 * fq;
; #pragma unroll
;         for (int ai = 0; ai < 2; ++ai)
; #pragma unroll
;             for (int m = 0; m < 4; ++m) { const int row = row0 + ai * 128 + m * 16;
; #pragma unroll
;                 for (int bj = 0; bj < 2; ++bj) { const int col = col0 + bj * 128; const u32x4 gw = *(const u32x4*)(G + ((size_t)(col >> 4) * MX + row) * 16 + (col & 15)); const f32x4 a = acc[ai][bj][m][0], b = acc[ai][bj][m][1];
;                     u32x4 w; w.x = cvt_pk_bf16(bf2f(gw.x & 0xffffu) * fast_sigmoid(a[0]), bf2f(gw.x >> 16) * fast_sigmoid(a[1])); w.y = cvt_pk_bf16(bf2f(gw.y & 0xffffu) * fast_sigmoid(a[2]), bf2f(gw.y >> 16) * fast_sigmoid(a[3]));
;                     w.z = cvt_pk_bf16(bf2f(gw.z & 0xffffu) * fast_sigmoid(b[0]), bf2f(gw.z >> 16) * fast_sigmoid(b[1])); w.w = cvt_pk_bf16(bf2f(gw.w & 0xffffu) * fast_sigmoid(b[2]), bf2f(gw.w >> 16) * fast_sigmoid(b[3]));
;                     *(u32x4*)(MIX + (size_t)row * 1024 + 512 + col) = w; } }
	v_lshlrev_b32_e32 v208, 16, v200
	v_and_b32_e32 v209, 0xffff0000, v200
	v_lshlrev_b32_e32 v210, 16, v201
	v_and_b32_e32 v211, 0xffff0000, v201
	v_lshlrev_b32_e32 v212, 16, v202
	v_and_b32_e32 v213, 0xffff0000, v202
	v_lshlrev_b32_e32 v214, 16, v203
	v_and_b32_e32 v215, 0xffff0000, v203
	v_pk_mul_f32 v[146:147], v[36:37], vcc
	v_pk_mul_f32 v[148:149], v[38:39], vcc
	v_exp_f32_e32 v146, v146
	v_exp_f32_e32 v147, v147
	v_exp_f32_e32 v148, v148
	v_exp_f32_e32 v149, v149
	v_pk_add_f32 v[146:147], v[146:147], 1.0 op_sel_hi:[1,0]
	v_pk_add_f32 v[148:149], v[148:149], 1.0 op_sel_hi:[1,0]
	v_rcp_f32_e32 v146, v146
	v_rcp_f32_e32 v147, v147
	v_rcp_f32_e32 v148, v148
	v_rcp_f32_e32 v149, v149
	v_pk_mul_f32 v[36:37], v[146:147], v[208:209]
	v_pk_mul_f32 v[38:39], v[148:149], v[210:211]
	v_pk_mul_f32 v[146:147], v[32:33], vcc
	v_pk_mul_f32 v[148:149], v[34:35], vcc
	v_exp_f32_e32 v146, v146
	v_exp_f32_e32 v147, v147
	v_exp_f32_e32 v148, v148
	v_exp_f32_e32 v149, v149
	v_pk_add_f32 v[146:147], v[146:147], 1.0 op_sel_hi:[1,0]
	v_pk_add_f32 v[148:149], v[148:149], 1.0 op_sel_hi:[1,0]
	v_rcp_f32_e32 v146, v146
	v_rcp_f32_e32 v147, v147
	v_rcp_f32_e32 v148, v148
	v_rcp_f32_e32 v149, v149
	v_pk_mul_f32 v[32:33], v[146:147], v[212:213]
	v_pk_mul_f32 v[34:35], v[148:149], v[214:215]
	v_cvt_pk_bf16_f32 v36, v36, v37
	v_cvt_pk_bf16_f32 v37, v38, v39
	v_cvt_pk_bf16_f32 v38, v32, v33
	v_cvt_pk_bf16_f32 v39, v34, v35
	s_waitcnt vmcnt(3)
	v_lshlrev_b32_e32 v208, 16, v156
	v_and_b32_e32 v209, 0xffff0000, v156
	v_lshlrev_b32_e32 v210, 16, v157
	v_and_b32_e32 v211, 0xffff0000, v157
	v_lshlrev_b32_e32 v212, 16, v158
	v_and_b32_e32 v213, 0xffff0000, v158
	v_lshlrev_b32_e32 v214, 16, v159
	v_and_b32_e32 v215, 0xffff0000, v159
	v_pk_mul_f32 v[146:147], v[28:29], vcc
	v_pk_mul_f32 v[148:149], v[30:31], vcc
	v_exp_f32_e32 v146, v146
	v_exp_f32_e32 v147, v147
	v_exp_f32_e32 v148, v148
	v_exp_f32_e32 v149, v149
	v_pk_add_f32 v[146:147], v[146:147], 1.0 op_sel_hi:[1,0]
	v_pk_add_f32 v[148:149], v[148:149], 1.0 op_sel_hi:[1,0]
	v_rcp_f32_e32 v146, v146
	v_rcp_f32_e32 v147, v147
	v_rcp_f32_e32 v148, v148
	v_rcp_f32_e32 v149, v149
	v_pk_mul_f32 v[28:29], v[146:147], v[208:209]
	v_pk_mul_f32 v[30:31], v[148:149], v[210:211]
	v_pk_mul_f32 v[146:147], v[24:25], vcc
	v_pk_mul_f32 v[148:149], v[26:27], vcc
	v_exp_f32_e32 v146, v146
	v_exp_f32_e32 v147, v147
	v_exp_f32_e32 v148, v148
	v_exp_f32_e32 v149, v149
	v_pk_add_f32 v[146:147], v[146:147], 1.0 op_sel_hi:[1,0]
	v_pk_add_f32 v[148:149], v[148:149], 1.0 op_sel_hi:[1,0]
	v_rcp_f32_e32 v146, v146
	v_rcp_f32_e32 v147, v147
	v_rcp_f32_e32 v148, v148
	v_rcp_f32_e32 v149, v149
	v_pk_mul_f32 v[24:25], v[146:147], v[212:213]
	v_pk_mul_f32 v[26:27], v[148:149], v[214:215]
	v_cvt_pk_bf16_f32 v28, v28, v29
	v_cvt_pk_bf16_f32 v29, v30, v31
	v_cvt_pk_bf16_f32 v30, v24, v25
	v_cvt_pk_bf16_f32 v31, v26, v27
	s_waitcnt vmcnt(2)
	v_lshlrev_b32_e32 v208, 16, v160
	v_and_b32_e32 v209, 0xffff0000, v160
	v_lshlrev_b32_e32 v210, 16, v161
	v_and_b32_e32 v211, 0xffff0000, v161
	v_lshlrev_b32_e32 v212, 16, v162
	v_and_b32_e32 v213, 0xffff0000, v162
	v_lshlrev_b32_e32 v214, 16, v163
	v_and_b32_e32 v215, 0xffff0000, v163
	v_pk_mul_f32 v[146:147], v[20:21], vcc
	v_pk_mul_f32 v[148:149], v[22:23], vcc
	v_exp_f32_e32 v146, v146
	v_exp_f32_e32 v147, v147
	v_exp_f32_e32 v148, v148
	v_exp_f32_e32 v149, v149
	v_pk_add_f32 v[146:147], v[146:147], 1.0 op_sel_hi:[1,0]
	v_pk_add_f32 v[148:149], v[148:149], 1.0 op_sel_hi:[1,0]
	v_rcp_f32_e32 v146, v146
	v_rcp_f32_e32 v147, v147
	v_rcp_f32_e32 v148, v148
	v_rcp_f32_e32 v149, v149
	v_pk_mul_f32 v[20:21], v[146:147], v[208:209]
	v_pk_mul_f32 v[22:23], v[148:149], v[210:211]
	v_pk_mul_f32 v[146:147], v[16:17], vcc
	v_pk_mul_f32 v[148:149], v[18:19], vcc
	v_exp_f32_e32 v146, v146
	v_exp_f32_e32 v147, v147
	v_exp_f32_e32 v148, v148
	v_exp_f32_e32 v149, v149
	v_pk_add_f32 v[146:147], v[146:147], 1.0 op_sel_hi:[1,0]
	v_pk_add_f32 v[148:149], v[148:149], 1.0 op_sel_hi:[1,0]
	v_rcp_f32_e32 v146, v146
	v_rcp_f32_e32 v147, v147
	v_rcp_f32_e32 v148, v148
	v_rcp_f32_e32 v149, v149
	v_pk_mul_f32 v[16:17], v[146:147], v[212:213]
	v_pk_mul_f32 v[18:19], v[148:149], v[214:215]
	v_cvt_pk_bf16_f32 v20, v20, v21
	v_cvt_pk_bf16_f32 v21, v22, v23
	v_cvt_pk_bf16_f32 v22, v16, v17
	v_cvt_pk_bf16_f32 v23, v18, v19
	s_waitcnt vmcnt(1)
; __device__ __forceinline__ unsigned cvt_pk_bf16(float lo, float hi) { unsigned r; asm("v_cvt_pk_bf16_f32 %0, %1, %2" : "=v"(r) : "v"(lo), "v"(hi)); return r; }
; __device__ __forceinline__ float fast_sigmoid(float x) { return __builtin_amdgcn_rcpf(1.0f + __builtin_amdgcn_exp2f(-x * LOG2E)); }
;     __device__ __forceinline__ void operator()(const Acc& acc, const Unit& u, int wr, int wc, int fr, int fq) const {
;         const int row0 = u.pm * 256 + wr * 64 + fr, col0 = u.pn * 256 + wc * 32 + 8 * fq;
; #pragma unroll
;         for (int ai = 0; ai < 2; ++ai)
; #pragma unroll
;             for (int m = 0; m < 4; ++m) { const int row = row0 + ai * 128 + m * 16;
; #pragma unroll
;                 for (int bj = 0; bj < 2; ++bj) { const int col = col0 + bj * 128; const u32x4 gw = *(const u32x4*)(G + ((size_t)(col >> 4) * MX + row) * 16 + (col & 15)); const f32x4 a = acc[ai][bj][m][0], b = acc[ai][bj][m][1];
;                     u32x4 w; w.x = cvt_pk_bf16(bf2f(gw.x & 0xffffu) * fast_sigmoid(a[0]), bf2f(gw.x >> 16) * fast_sigmoid(a[1])); w.y = cvt_pk_bf16(bf2f(gw.y & 0xffffu) * fast_sigmoid(a[2]), bf2f(gw.y >> 16) * fast_sigmoid(a[3]));
;                     w.z = cvt_pk_bf16(bf2f(gw.z & 0xffffu) * fast_sigmoid(b[0]), bf2f(gw.z >> 16) * fast_sigmoid(b[1])); w.w = cvt_pk_bf16(bf2f(gw.w & 0xffffu) * fast_sigmoid(b[2]), bf2f(gw.w >> 16) * fast_sigmoid(b[3]));
;                     *(u32x4*)(MIX + (size_t)row * 1024 + 512 + col) = w; } }
	v_lshlrev_b32_e32 v208, 16, v164
	v_and_b32_e32 v209, 0xffff0000, v164
	v_lshlrev_b32_e32 v210, 16, v165
	v_and_b32_e32 v211, 0xffff0000, v165
	v_lshlrev_b32_e32 v212, 16, v166
	v_and_b32_e32 v213, 0xffff0000, v166
	v_lshlrev_b32_e32 v214, 16, v167
	v_and_b32_e32 v215, 0xffff0000, v167
	v_pk_mul_f32 v[146:147], v[12:13], vcc
	v_pk_mul_f32 v[148:149], v[14:15], vcc
	v_exp_f32_e32 v146, v146
	v_exp_f32_e32 v147, v147
	v_exp_f32_e32 v148, v148
	v_exp_f32_e32 v149, v149
	v_pk_add_f32 v[146:147], v[146:147], 1.0 op_sel_hi:[1,0]
	v_pk_add_f32 v[148:149], v[148:149], 1.0 op_sel_hi:[1,0]
	v_rcp_f32_e32 v146, v146
	v_rcp_f32_e32 v147, v147
	v_rcp_f32_e32 v148, v148
	v_rcp_f32_e32 v149, v149
	v_pk_mul_f32 v[12:13], v[146:147], v[208:209]
	v_pk_mul_f32 v[14:15], v[148:149], v[210:211]
	v_pk_mul_f32 v[146:147], v[8:9], vcc
	v_pk_mul_f32 v[148:149], v[10:11], vcc
	v_exp_f32_e32 v146, v146
	v_exp_f32_e32 v147, v147
	v_exp_f32_e32 v148, v148
	v_exp_f32_e32 v149, v149
	v_pk_add_f32 v[146:147], v[146:147], 1.0 op_sel_hi:[1,0]
	v_pk_add_f32 v[148:149], v[148:149], 1.0 op_sel_hi:[1,0]
	v_rcp_f32_e32 v146, v146
	v_rcp_f32_e32 v147, v147
	v_rcp_f32_e32 v148, v148
	v_rcp_f32_e32 v149, v149
	v_pk_mul_f32 v[8:9], v[146:147], v[212:213]
	v_pk_mul_f32 v[10:11], v[148:149], v[214:215]
	v_cvt_pk_bf16_f32 v12, v12, v13
	v_cvt_pk_bf16_f32 v13, v14, v15
	v_cvt_pk_bf16_f32 v14, v8, v9
	v_cvt_pk_bf16_f32 v15, v10, v11
	s_waitcnt vmcnt(0)
	v_lshlrev_b32_e32 v208, 16, v168
	v_and_b32_e32 v209, 0xffff0000, v168
	v_lshlrev_b32_e32 v210, 16, v169
	v_and_b32_e32 v211, 0xffff0000, v169
	v_lshlrev_b32_e32 v212, 16, v170
	v_and_b32_e32 v213, 0xffff0000, v170
	v_lshlrev_b32_e32 v214, 16, v171
	v_and_b32_e32 v215, 0xffff0000, v171
	v_pk_mul_f32 v[146:147], v[4:5], vcc
	v_pk_mul_f32 v[148:149], v[6:7], vcc
	v_exp_f32_e32 v146, v146
	v_exp_f32_e32 v147, v147
	v_exp_f32_e32 v148, v148
	v_exp_f32_e32 v149, v149
	v_pk_add_f32 v[146:147], v[146:147], 1.0 op_sel_hi:[1,0]
	v_pk_add_f32 v[148:149], v[148:149], 1.0 op_sel_hi:[1,0]
	v_rcp_f32_e32 v146, v146
	v_rcp_f32_e32 v147, v147
	v_rcp_f32_e32 v148, v148
	v_rcp_f32_e32 v149, v149
	v_pk_mul_f32 v[4:5], v[146:147], v[208:209]
	v_pk_mul_f32 v[6:7], v[148:149], v[210:211]
	v_pk_mul_f32 v[146:147], v[0:1], vcc
	v_pk_mul_f32 v[148:149], v[2:3], vcc
	v_exp_f32_e32 v146, v146
	v_exp_f32_e32 v147, v147
	v_exp_f32_e32 v148, v148
	v_exp_f32_e32 v149, v149
	v_pk_add_f32 v[146:147], v[146:147], 1.0 op_sel_hi:[1,0]
	v_pk_add_f32 v[148:149], v[148:149], 1.0 op_sel_hi:[1,0]
	v_rcp_f32_e32 v146, v146
	v_rcp_f32_e32 v147, v147
	v_rcp_f32_e32 v148, v148
	v_rcp_f32_e32 v149, v149
	v_pk_mul_f32 v[0:1], v[146:147], v[212:213]
	v_pk_mul_f32 v[2:3], v[148:149], v[214:215]
	v_cvt_pk_bf16_f32 v4, v4, v5
	v_cvt_pk_bf16_f32 v5, v6, v7
	v_cvt_pk_bf16_f32 v6, v0, v1
	v_cvt_pk_bf16_f32 v7, v2, v3
	global_store_dwordx4 v218, v[124:127], s[6:7] offset:1024
	global_store_dwordx4 v218, v[116:119], s[6:7] offset:1280
	v_add_u32_e32 v216, 0x8000, v218
	global_store_dwordx4 v216, v[108:111], s[6:7] offset:1024
	global_store_dwordx4 v216, v[100:103], s[6:7] offset:1280
	v_add_u32_e32 v217, 0x10000, v218
	global_store_dwordx4 v217, v[92:95], s[6:7] offset:1024
	global_store_dwordx4 v217, v[84:87], s[6:7] offset:1280
	v_add_u32_e32 v216, 0x18000, v218
	global_store_dwordx4 v216, v[76:79], s[6:7] offset:1024
	global_store_dwordx4 v216, v[68:71], s[6:7] offset:1280
	v_add_u32_e32 v217, 0x40000, v218
	global_store_dwordx4 v217, v[60:63], s[6:7] offset:1024
	global_store_dwordx4 v217, v[52:55], s[6:7] offset:1280
	v_add_u32_e32 v216, 0x48000, v218
	global_store_dwordx4 v216, v[44:47], s[6:7] offset:1024
	global_store_dwordx4 v216, v[36:39], s[6:7] offset:1280
	v_add_u32_e32 v217, 0x50000, v218
	global_store_dwordx4 v217, v[28:31], s[6:7] offset:1024
	global_store_dwordx4 v217, v[20:23], s[6:7] offset:1280
	v_add_u32_e32 v216, 0x58000, v218
	global_store_dwordx4 v216, v[12:15], s[6:7] offset:1024
	global_store_dwordx4 v216, v[4:7], s[6:7] offset:1280
	s_andn2_b64 vcc, exec, s[4:5]
	s_mov_b64 s[4:5], -1
	s_cbranch_vccnz .LBB0_834
	s_andn2_b64 vcc, exec, s[8:9]
	s_cbranch_vccnz .LBB0_833
	s_barrier
	s_branch .LBB0_833
